# split barrier between the scan/attention phase and ret_output: arrive after ret_scan (L2 write-back + counter), wait before ret_output, so early workgroups start ret_output while boundary-block workgr
# speedup vs baseline: 1.0016x; 1.0016x over previous
; #define LAS __attribute__((address_space(3)))
; __device__ __forceinline__ void weights_prologue(Frame& F, const float* const (&in)[14]) {
;     ...
;         TrItem tc, tn; float wa[32], wb[32]; int it = F.gw;
;         if (it < NL * I_LAYER) { decode(it, tc); tr_load(tc, F.lane, wa); }
;         while (it < NL * I_LAYER) {
;             const int itn = it + F.NGW; const bool more = itn < NL * I_LAYER;
;             if (more) { decode(itn, tn); tr_load(tn, F.lane, wb); }
; __global__ void __launch_bounds__(NTHR, 2) mega_fwd(Args args) {
;     ...
;     const int wave_s = __builtin_amdgcn_readfirstlane((int)threadIdx.x >> 6);
;     ...
;     const int lo = args.ph_lo, hi = args.ph_hi; int ph = 0;
;     ...
;     if (MYTID < 16) ((LAS unsigned*)(lds_raw + RING_BYTES))[MYTID] = 0u;
;     if (blockIdx.x == 0) { for (int i = MYTID; i < 4096; i += NTHR) ((unsigned*)args.ws)[i] = 0u; }
;     __syncthreads();
;     ...
;     if (PH_ON) { MKF; const int tr = 0; MKT; weights_prologue(F, args.in); trunk_prologue(F, T); }
.LBB0_12:
	s_load_dwordx16 s[68:83], s[0:1], 0x0
	s_mov_b32 s101, 0
	s_waitcnt lgkmcnt(0)
	s_cmp_lt_i32 s20, 1
	s_cselect_b64 s[6:7], -1, 0
	s_cmp_gt_i32 s21, 0
	s_cselect_b64 s[2:3], -1, 0
	s_and_b64 s[2:3], s[6:7], s[2:3]
	s_andn2_b64 vcc, exec, s[2:3]
	s_mov_b32 s2, 0
	v_writelane_b32 v254, s56, 0
	s_barrier
	s_cbranch_vccnz .LBB0_113
	s_mov_b32 s9, s18
	v_mbcnt_lo_u32_b32 v2, -1, s2
	v_mbcnt_hi_u32_b32 v2, -1, v2
	v_add_u32_e32 v75, s56, v2
	s_mov_b64 s[4:5], 0
	v_readfirstlane_b32 s2, v75
	s_ashr_i32 s34, s2, 6
	s_lshl_b32 s2, s9, 3
	s_add_i32 s8, s34, s2
	s_add_u32 s2, s50, s4
	v_and_b32_e32 v74, 63, v75
	s_addc_u32 s3, s51, s5
	s_mov_b64 s[10:11], 0
	s_cmp_lt_i32 s8, 0xbc00
	v_lshrrev_b32_e32 v7, 5, v74
	v_and_b32_e32 v2, 31, v75
	s_cbranch_scc1 .LBB0_16
	v_lshrrev_b32_e32 v3, 5, v74
	v_and_b32_e32 v4, 31, v75
	v_mov_b32_e32 v5, 0
	s_andn2_b64 vcc, exec, s[10:11]
	s_cbranch_vccz .LBB0_17
	v_mov_b32_e32 v10, 0
	v_mov_b32_e32 v11, v10
	v_mov_b32_e32 v12, v10
	v_mov_b32_e32 v13, v10
	v_mov_b32_e32 v14, v10
	v_mov_b32_e32 v15, v10
	v_mov_b32_e32 v16, v10
	v_mov_b32_e32 v17, v10
	v_mov_b32_e32 v18, v10
	v_mov_b32_e32 v19, v10
	v_mov_b32_e32 v20, v10
	v_mov_b32_e32 v21, v10
	v_mov_b32_e32 v22, v10
	v_mov_b32_e32 v23, v10
	v_mov_b32_e32 v24, v10
	v_mov_b32_e32 v25, v10
	v_mov_b32_e32 v26, v10
	v_mov_b32_e32 v27, v10
	v_mov_b32_e32 v28, v10
	v_mov_b32_e32 v29, v10
	v_mov_b32_e32 v30, v10
	v_mov_b32_e32 v31, v10
	v_mov_b32_e32 v32, v10
	v_mov_b32_e32 v33, v10
	v_mov_b32_e32 v50, v10
	v_mov_b32_e32 v51, v10
	v_mov_b32_e32 v52, v10
	v_mov_b32_e32 v53, v10
	v_mov_b32_e32 v54, v10
	v_mov_b32_e32 v55, v10
	v_mov_b32_e32 v56, v10
	v_mov_b32_e32 v57, v10
	v_mov_b32_e32 v7, v3
	v_mov_b32_e32 v2, v4
	s_branch .LBB0_28

; __global__ void __launch_bounds__(NTHR, 2) mega_fwd(Args args) {
;     ...
;             if (PH_ON) { MKF; MKT; ret_scan(F, T, layer); for (int rp = 0; rp < RPT_AC; ++rp) { if (F.G == 256) mixer_a2(F, T); else mixer_a(F, T); mixer_c(F, T, layer); } }
.LBB0_472:
	s_waitcnt vmcnt(0)
	s_barrier
	s_add_i32 s101, s101, 0x100
	v_readlane_b32 s98, v254, 0
	s_nop 3
	s_cmp_lg_u32 s98, 0
	s_cbranch_scc1 .Lsplit_arrive_done
	s_mov_b64 s[98:99], exec
	s_mov_b64 exec, 1
	buffer_wbl2 sc1
	s_waitcnt vmcnt(0)
	v_mov_b32_e32 v166, 0x3840
	v_mov_b32_e32 v168, 1
	global_atomic_add v166, v168, s[50:51]
	s_mov_b64 exec, s[98:99]

; __device__ __forceinline__ unsigned xb_ld(unsigned* p)              { return __hip_atomic_load(p, __ATOMIC_RELAXED, __HIP_MEMORY_SCOPE_AGENT); }
; __device__ __forceinline__ unsigned xb_add(unsigned* p, unsigned v) { return __hip_atomic_fetch_add(p, v, __ATOMIC_RELAXED, __HIP_MEMORY_SCOPE_AGENT); }
; #define XB_SPIN(cond, bar) do { unsigned _sp = 0; while (cond) { __builtin_amdgcn_s_sleep(1); \
;     if ((++_sp & 255u) == 0u) { if (xb_ld(&(bar)[XB_TMO])) break; if (_sp > XB_SPIN_CAP) { atomicAdd(&(bar)[XB_TMO], 1u); break; } } } } while (0)
; __device__ __forceinline__ void xcd_barrier(const XcdBarrier& b, bool is_t0) {
;     asm volatile("s_waitcnt vmcnt(0)" ::: "memory");
;     __syncthreads();
;     if (is_t0) {
;         unsigned* bar = b.bar;
;         __builtin_amdgcn_s_waitcnt(0);
;         unsigned nloc = b.st[0], nx = b.st[1];
;         if (nloc == 0u) { xcd_barrier_complete(bar, b.x, nloc, nx); b.st[0] = nloc; b.st[1] = nx; }
;         const unsigned old = xb_add(&bar[XB_XSUB(b.x)], 1u);
;         const unsigned gen = old / nloc;
;         if (old + 1u == (gen + 1u) * nloc) {
;             __builtin_amdgcn_fence(__ATOMIC_RELEASE, "agent");
;             asm volatile("s_waitcnt vmcnt(0)" ::: "memory");
;             const unsigned og = xb_add(&bar[XB_TOP], 1u);
;             const unsigned tg = og / nx;
;             if (og + 1u == (tg + 1u) * nx) xb_add(&bar[XB_TOPGEN], 1u);
;             else XB_SPIN(xb_ld(&bar[XB_TOPGEN]) == tg, bar);
;             __builtin_amdgcn_fence(__ATOMIC_ACQUIRE, "agent");
;             xb_add(&bar[XB_XGEN(b.x)], 1u);
;             asm volatile("s_waitcnt vmcnt(0)" ::: "memory");
;         } else {
;             XB_SPIN(xb_ld(&bar[XB_XGEN(b.x)]) == gen, bar);
;             __builtin_amdgcn_fence(__ATOMIC_ACQUIRE, "agent");
;             asm volatile("s_waitcnt vmcnt(0)" ::: "memory");
;         }
.LBB0_651:
	s_add_i32 s30, s53, 3
	s_cmp_lt_i32 s30, s21
	v_readlane_b32 s2, v255, 59
	s_cselect_b64 s[0:1], -1, 0
	v_readlane_b32 s3, v255, 60
	s_and_b64 s[2:3], s[2:3], s[0:1]
	s_andn2_b64 vcc, exec, s[2:3]
	s_cbranch_vccnz .LBB0_721
	s_cmp_lg_u32 s85, 0
	s_cbranch_scc0 .LBB0_664
	s_mov_b32 s2, s61
	s_getreg_b32 s4, hwreg(HW_REG_XCC_ID, 0, 4)
	s_waitcnt vmcnt(0)
	s_waitcnt lgkmcnt(0)
	v_mbcnt_lo_u32_b32 v0, -1, s2
	v_mbcnt_hi_u32_b32 v0, -1, v0
	v_sub_u32_e32 v0, 0, v0
	v_cmp_eq_u32_e32 vcc, s56, v0
	s_barrier
	s_and_saveexec_b64 s[2:3], vcc
	s_cbranch_execz .LBB0_706
	v_mov_b32_e32 v0, 0x3840
	s_movk_i32 s4, 0x3ff
.Lsplit_wait_loop:
	global_load_dword v1, v0, s[50:51] sc1
	s_waitcnt vmcnt(0)
	v_cmp_le_u32_e32 vcc, s101, v1
	s_cbranch_vccnz .Lsplit_wait_done
	s_sleep 1
	s_sub_i32 s4, s4, 1
	s_cmp_gt_i32 s4, 0
	s_cbranch_scc1 .Lsplit_wait_loop
.Lsplit_wait_done:
	buffer_inv sc1
	s_waitcnt vmcnt(0)
	s_branch .LBB0_706
	s_add_i32 s11, 0, 0x20000
	v_mov_b32_e32 v0, s11
	s_waitcnt vmcnt(0) expcnt(0) lgkmcnt(0)
	ds_read_b32 v2, v0
	v_readlane_b32 s5, v254, 50
	s_and_b32 s10, s4, 15
	s_waitcnt lgkmcnt(0)
	v_cmp_ne_u32_e32 vcc, 0, v2
	v_mov_b32_e32 v0, s5
	ds_read_b32 v0, v0
	s_cbranch_vccnz .LBB0_670
	v_readlane_b32 s6, v254, 17
	v_readlane_b32 s7, v254, 18
	s_load_dwordx2 s[4:5], s[6:7], 0x0
	s_nop 0
	s_load_dword s6, s[6:7], 0x8
	s_mov_b32 s13, 1
	s_waitcnt lgkmcnt(0)
	s_mul_i32 s12, s5, s4
	s_mul_i32 s12, s12, s6
	s_branch .LBB0_657
